# chain: static s_setprio 1 moved to waves 0-3 (other-half A/B of the existing waves 4-7 raise)
# baseline (speedup 1.0000x reference)
.LBB0_500:
	s_andn2_b64 vcc, exec, s[2:3]
	s_cbranch_vccnz .LBB0_505
	s_cmp_gt_u32 s20, 63
	s_cbranch_scc1 .LBB0_505
	s_lshr_b32 s4, s20, 3
	s_bfe_u32 s12, s20, 0x20001
	s_and_b32 s14, s20, 1
	s_bfe_i32 s5, s20, 0x10000
	s_lshl_b32 s15, s4, 2
	s_add_u32 s8, s22, 0x2cbc000
	s_addc_u32 s9, s23, 0
	s_lshl_b32 s2, s12, 2
	s_lshl_b32 s3, s14, 4
	s_or_b32 s2, s3, s2
	s_waitcnt vmcnt(0)
	v_mov_b32_e32 v0, s2
	global_load_dword v1, v0, s[54:55]
	s_mov_b32 s10, 0x3f2aaaab
	v_mov_b32_e32 v16, 0x3ecc95a3
	v_mov_b32_e32 v0, 0x3f317218
	s_mov_b32 s11, 0x3f317218
	s_mov_b32 s13, 0xff800000
	v_mov_b32_e32 v22, 0x7f800000
	v_mov_b32_e32 v23, 0x7fc00000
	v_mov_b32_e32 v24, 0xff800000
	s_mov_b32 s25, 0x33800000
	v_lshrrev_b32_e32 v84, 4, v160
	s_cmp_eq_u32 s14, 0
	v_xor_b32_e32 v25, 0x7f, v84
	s_cselect_b64 s[2:3], -1, 0
	s_lshl_b32 s16, s4, 19
	s_lshl_b32 s17, s14, 18
	s_and_b32 s5, s5, 0xf80
	s_or_b32 s26, s16, s17
	s_add_u32 s16, s8, s26
	s_addc_u32 s17, s9, 0
	s_lshl_b32 s24, s12, 8
	v_and_b32_e32 v99, 15, v160
	s_add_u32 s16, s16, s24
	v_mov_b32_e32 v97, 0
	v_lshlrev_b32_e32 v96, 4, v99
	s_addc_u32 s17, s17, 0
	v_lshlrev_b32_e32 v2, 11, v84
	v_mov_b32_e32 v3, v97
	v_lshl_add_u64 v[4:5], s[16:17], 0, v[96:97]
	v_lshl_add_u64 v[6:7], v[4:5], 0, v[2:3]
	global_load_dwordx4 v[32:35], v[6:7], off
	global_load_dwordx4 v[36:39], v[6:7], off offset:1024
	v_add_u32_e32 v118, 0, v96
	v_bfe_u32 v146, v160, 6, 2
	v_lshrrev_b32_e32 v147, 8, v160
	v_bfe_u32 v64, v160, 2, 2
	v_lshlrev_b32_e32 v148, 3, v84
	v_lshlrev_b32_e32 v149, 7, v147
	v_lshlrev_b32_e32 v151, 6, v146
	v_and_or_b32 v152, v148, 24, v64
	v_mov_b32_e32 v117, v97
	v_mul_u32_u24_e32 v123, 0x130, v84
	s_waitcnt vmcnt(0)
	v_mul_f32_e32 v1, 0x3fb8aa3b, v1
	v_exp_f32_e32 v26, v1
	s_nop 0
	v_sub_f32_e32 v1, 1.0, v26
	v_add_f32_e32 v10, -1.0, v1
	v_frexp_mant_f32_e32 v11, v1
	v_cvt_f64_f32_e32 v[8:9], v1
	v_sub_f32_e32 v12, v10, v1
	v_frexp_exp_i32_f64_e32 v8, v[8:9]
	v_cmp_gt_f32_e32 vcc, s10, v11
	v_sub_f32_e64 v10, -v26, v10
	v_add_f32_e32 v9, 1.0, v12
	v_subbrev_co_u32_e32 v8, vcc, 0, v8, vcc
	v_add_f32_e32 v9, v10, v9
	v_sub_u32_e32 v10, 0, v8
	v_ldexp_f32 v1, v1, v10
	v_ldexp_f32 v9, v9, v10
	v_add_f32_e32 v10, -1.0, v1
	v_add_f32_e32 v12, 1.0, v1
	v_add_f32_e32 v11, 1.0, v10
	v_add_f32_e32 v13, -1.0, v12
	v_sub_f32_e32 v11, v1, v11
	v_sub_f32_e32 v1, v1, v13
	v_add_f32_e32 v1, v9, v1
	v_add_f32_e32 v13, v9, v11
	v_add_f32_e32 v9, v12, v1
	v_rcp_f32_e32 v17, v9
	v_add_f32_e32 v11, v10, v13
	v_sub_f32_e32 v12, v9, v12
	v_sub_f32_e32 v1, v1, v12
	v_mul_f32_e32 v19, v11, v17
	v_mul_f32_e32 v12, v9, v19
	v_fma_f32 v14, v19, v9, -v12
	v_sub_f32_e32 v10, v11, v10
	v_fmac_f32_e32 v14, v19, v1
	v_sub_f32_e32 v18, v13, v10
	v_add_f32_e32 v10, v12, v14
	v_sub_f32_e32 v13, v11, v10
	v_mov_b32_e32 v15, v10
	v_pk_add_f32 v[10:11], v[10:11], v[12:13] neg_lo:[0,1] neg_hi:[0,1]
	v_cvt_f32_i32_e32 v8, v8
	v_pk_add_f32 v[10:11], v[10:11], v[14:15] neg_lo:[0,1] neg_hi:[0,1]
	v_cmp_neq_f32_e32 vcc, s13, v26
	v_add_f32_e32 v11, v18, v11
	v_add_f32_e32 v10, v10, v11
	v_add_f32_e32 v11, v13, v10
	v_mul_f32_e32 v15, v17, v11
	v_mul_f32_e32 v12, v9, v15
	v_fma_f32 v14, v15, v9, -v12
	v_sub_f32_e32 v13, v13, v11
	v_fmac_f32_e32 v14, v15, v1
	v_add_f32_e32 v18, v10, v13
	v_add_f32_e32 v20, v19, v15
	v_add_f32_e32 v10, v12, v14
	v_sub_f32_e32 v9, v20, v19
	v_sub_f32_e32 v13, v11, v10
	v_sub_f32_e32 v1, v15, v9
	v_mov_b32_e32 v15, v10
	v_pk_add_f32 v[10:11], v[10:11], v[12:13] neg_lo:[0,1] neg_hi:[0,1]
	s_nop 0
	v_pk_add_f32 v[10:11], v[10:11], v[14:15] neg_lo:[0,1] neg_hi:[0,1]
	s_nop 0
	v_add_f32_e32 v9, v18, v11
	v_add_f32_e32 v9, v10, v9
	v_add_f32_e32 v9, v13, v9
	v_mul_f32_e32 v9, v17, v9
	v_add_f32_e32 v1, v1, v9
	v_add_f32_e32 v9, v20, v1
	v_mul_f32_e32 v10, v9, v9
	v_sub_f32_e32 v12, v9, v20
	v_fmac_f32_e32 v16, 0x3e9b6dac, v10
	v_ldexp_f32 v11, v9, 1
	v_sub_f32_e32 v12, v1, v12
	v_mul_f32_e32 v9, v9, v10
	v_fmaak_f32 v1, v10, v16, 0x3f2aaada
	v_pk_mul_f32 v[0:1], v[8:9], v[0:1]
	v_ldexp_f32 v13, v12, 1
	v_fma_f32 v9, v8, s11, -v0
	v_fmamk_f32 v10, v8, 0xb102e308, v9
	v_pk_add_f32 v[8:9], v[0:1], v[10:11]
	v_mov_b32_e32 v12, v0
	v_sub_f32_e32 v16, v9, v11
	v_pk_add_f32 v[14:15], v[8:9], v[0:1] neg_lo:[0,1] neg_hi:[0,1]
	v_sub_f32_e32 v1, v1, v16
	v_add_f32_e32 v13, v13, v1
	v_pk_add_f32 v[18:19], v[8:9], v[12:13]
	v_mov_b32_e32 v11, v8
	v_mov_b32_e32 v15, v19
	v_pk_add_f32 v[20:21], v[10:11], v[14:15] neg_lo:[0,1] neg_hi:[0,1]
	v_pk_add_f32 v[10:11], v[10:11], v[14:15]
	v_mov_b32_e32 v0, v9
	v_mov_b32_e32 v17, v8
	v_pk_add_f32 v[8:9], v[10:11], v[8:9] op_sel:[1,0] op_sel_hi:[0,1] neg_lo:[0,1] neg_hi:[0,1]
	v_mov_b32_e32 v16, v13
	v_mov_b32_e32 v12, v19
	v_mov_b32_e32 v13, v11
	v_mov_b32_e32 v1, v8
	v_pk_add_f32 v[14:15], v[18:19], v[8:9] op_sel_hi:[1,0] neg_lo:[0,1] neg_hi:[0,1]
	v_pk_add_f32 v[0:1], v[12:13], v[0:1] neg_lo:[0,1] neg_hi:[0,1]
	v_mov_b32_e32 v14, v20
	v_pk_add_f32 v[0:1], v[16:17], v[0:1] neg_lo:[0,1] neg_hi:[0,1]
	v_mov_b32_e32 v21, v11
	v_pk_add_f32 v[8:9], v[14:15], v[0:1]
	v_cmp_lt_f32_e64 s[10:11], |v26|, s25
	v_pk_add_f32 v[12:13], v[8:9], v[8:9] op_sel:[0,1] op_sel_hi:[1,0]
	s_add_u32 s25, s22, 0x74bc000
	v_pk_add_f32 v[10:11], v[10:11], v[12:13] op_sel:[1,0] op_sel_hi:[0,1]
	v_mov_b32_e32 v9, v10
	v_mov_b32_e32 v1, v12
	v_pk_add_f32 v[12:13], v[8:9], v[20:21] neg_lo:[0,1] neg_hi:[0,1]
	s_addc_u32 s27, s23, 0
	v_sub_f32_e32 v8, v8, v12
	v_pk_add_f32 v[0:1], v[0:1], v[12:13] neg_lo:[0,1] neg_hi:[0,1]
	v_sub_f32_e32 v8, v20, v8
	v_add_f32_e32 v0, v0, v8
	v_add_f32_e32 v0, v0, v1
	v_add_f32_e32 v0, v10, v0
	v_cndmask_b32_e32 v0, v22, v0, vcc
	v_cmp_nlt_f32_e32 vcc, 1.0, v26
	v_sub_u32_e32 v1, 0x5f, v84
	s_xor_b32 s13, s26, 0x40000
	v_cndmask_b32_e32 v0, v23, v0, vcc
	v_cmp_neq_f32_e32 vcc, 1.0, v26
	s_add_u32 s8, s8, s13
	s_addc_u32 s9, s9, 0
	v_cndmask_b32_e32 v0, v24, v0, vcc
	v_cndmask_b32_e64 v8, v0, -v26, s[10:11]
	v_mul_f32_e32 v0, 0x43000000, v8
	v_mul_f32_e32 v0, 0x3fb8aa3b, v0
	v_exp_f32_e32 v98, v0
	v_cndmask_b32_e64 v0, v84, v25, s[2:3]
	v_cvt_f32_ubyte0_e32 v0, v0
	v_mul_f32_e32 v0, v8, v0
	v_mul_f32_e32 v0, 0x3fb8aa3b, v0
	v_exp_f32_e32 v100, v0
	v_add_u32_e32 v0, 32, v84
	v_cndmask_b32_e64 v0, v0, v1, s[2:3]
	v_cvt_f32_ubyte0_e32 v0, v0
	v_mul_f32_e32 v0, v8, v0
	v_mul_f32_e32 v0, 0x3fb8aa3b, v0
	v_exp_f32_e32 v102, v0
	v_or_b32_e32 v0, 64, v84
	v_xor_b32_e32 v1, 63, v84
	s_mov_b32 s10, 0x10000
	v_cndmask_b32_e64 v9, v0, v1, s[2:3]
	v_add_co_u32_e32 v0, vcc, s10, v6
	s_mov_b32 s11, 0x30000
	s_nop 0
	v_addc_co_u32_e32 v1, vcc, 0, v7, vcc
	global_load_dwordx4 v[40:43], v[0:1], off
	global_load_dwordx4 v[44:47], v[0:1], off offset:1024
	v_cvt_f32_ubyte0_e32 v0, v9
	v_sub_u32_e32 v1, 31, v84
	v_mul_f32_e32 v0, v8, v0
	v_cvt_f32_i32_e32 v1, v1
	v_mul_f32_e32 v0, 0x3fb8aa3b, v0
	v_exp_f32_e32 v104, v0
	v_add_u32_e32 v0, 0x60, v84
	v_cvt_f32_ubyte0_e32 v0, v0
	v_cndmask_b32_e64 v0, v0, v1, s[2:3]
	v_mul_f32_e32 v0, v0, v8
	v_mul_f32_e32 v0, 0x3fb8aa3b, v0
	v_exp_f32_e32 v106, v0
	v_or_b32_e32 v0, 0x20000, v2
	v_mov_b32_e32 v1, v97
	v_lshl_add_u64 v[4:5], v[4:5], 0, v[0:1]
	global_load_dwordx4 v[48:51], v[4:5], off
	global_load_dwordx4 v[52:55], v[4:5], off offset:1024
	v_add_co_u32_e32 v4, vcc, s11, v6
	s_add_u32 s8, s8, s24
	s_nop 0
	v_addc_co_u32_e32 v5, vcc, 0, v7, vcc
	global_load_dwordx4 v[56:59], v[4:5], off
	global_load_dwordx4 v[60:63], v[4:5], off offset:1024
	s_addc_u32 s9, s9, 0
	v_lshl_add_u64 v[4:5], s[8:9], 0, v[96:97]
	v_lshl_add_u64 v[2:3], v[4:5], 0, v[2:3]
	v_add_co_u32_e32 v6, vcc, s10, v2
	v_lshl_add_u64 v[0:1], v[4:5], 0, v[0:1]
	s_nop 0
	v_addc_co_u32_e32 v7, vcc, 0, v3, vcc
	global_load_dwordx4 v[28:31], v[2:3], off
	global_load_dwordx4 v[24:27], v[2:3], off offset:1024
	global_load_dwordx4 v[20:23], v[6:7], off
	global_load_dwordx4 v[16:19], v[6:7], off offset:1024
	global_load_dwordx4 v[12:15], v[0:1], off
	global_load_dwordx4 v[8:11], v[0:1], off offset:1024
	v_add_co_u32_e32 v0, vcc, s11, v2
	s_movk_i32 s8, 0x130
	s_nop 0
	v_addc_co_u32_e32 v1, vcc, 0, v3, vcc
	v_mad_u32_u24 v65, v84, s8, v118
	global_load_dwordx4 v[4:7], v[0:1], off
	s_nop 0
	global_load_dwordx4 v[0:3], v[0:1], off offset:1024
	ds_write_b128 v65, v[32:35]
	v_lshlrev_b32_e32 v32, 16, v36
	v_and_b32_e32 v33, 0xffff0000, v36
	v_mov_b32_e32 v101, v100
	v_lshlrev_b32_e32 v34, 16, v37
	v_and_b32_e32 v35, 0xffff0000, v37
	v_pk_mul_f32 v[32:33], v[100:101], v[32:33] op_sel_hi:[0,1]
	v_pk_mul_f32 v[34:35], v[100:101], v[34:35] op_sel_hi:[0,1]
	v_cvt_pk_bf16_f32 v32, v32, v33
	v_cvt_pk_bf16_f32 v33, v34, v35
	v_lshlrev_b32_e32 v34, 16, v38
	v_and_b32_e32 v35, 0xffff0000, v38
	v_lshlrev_b32_e32 v36, 16, v39
	v_and_b32_e32 v37, 0xffff0000, v39
	v_pk_mul_f32 v[34:35], v[100:101], v[34:35] op_sel_hi:[0,1]
	v_pk_mul_f32 v[36:37], v[100:101], v[36:37] op_sel_hi:[0,1]
	v_cvt_pk_bf16_f32 v34, v34, v35
	v_cvt_pk_bf16_f32 v35, v36, v37
	ds_write_b128 v65, v[32:35] offset:38912
	v_mov_b32_e32 v32, 0x2600
	v_mad_u32_u24 v32, v84, s8, v32
	v_add_u32_e32 v119, v118, v32
	v_mov_b32_e32 v103, v102
	v_mov_b32_e32 v105, v104
	v_mov_b32_e32 v107, v106
	s_lshl_b32 s16, s4, 12
	s_or_b32 s4, s5, s16
	s_mulk_i32 s4, 0x1c00
	s_add_u32 s4, s25, s4
	s_addc_u32 s5, s27, 0
	s_add_u32 s4, s4, s24
	s_addc_u32 s5, s5, 0
	s_mov_b64 s[10:11], 0xa8000
	s_mov_b32 s26, 1
	s_mov_b32 s13, 0
	s_waitcnt vmcnt(0)
	ds_write_b128 v119, v[40:43]
	v_lshlrev_b32_e32 v32, 16, v44
	v_and_b32_e32 v33, 0xffff0000, v44
	v_lshlrev_b32_e32 v34, 16, v45
	v_and_b32_e32 v35, 0xffff0000, v45
	v_pk_mul_f32 v[32:33], v[102:103], v[32:33] op_sel_hi:[0,1]
	v_pk_mul_f32 v[34:35], v[102:103], v[34:35] op_sel_hi:[0,1]
	v_cvt_pk_bf16_f32 v32, v32, v33
	v_cvt_pk_bf16_f32 v33, v34, v35
	v_lshlrev_b32_e32 v34, 16, v46
	v_and_b32_e32 v35, 0xffff0000, v46
	v_lshlrev_b32_e32 v36, 16, v47
	v_and_b32_e32 v37, 0xffff0000, v47
	v_pk_mul_f32 v[34:35], v[102:103], v[34:35] op_sel_hi:[0,1]
	v_pk_mul_f32 v[36:37], v[102:103], v[36:37] op_sel_hi:[0,1]
	v_cvt_pk_bf16_f32 v34, v34, v35
	v_cvt_pk_bf16_f32 v35, v36, v37
	ds_write_b128 v119, v[32:35] offset:38912
	ds_write_b128 v119, v[48:51] offset:9728
	v_lshlrev_b32_e32 v32, 16, v52
	v_and_b32_e32 v33, 0xffff0000, v52
	v_lshlrev_b32_e32 v34, 16, v53
	v_and_b32_e32 v35, 0xffff0000, v53
	v_pk_mul_f32 v[32:33], v[104:105], v[32:33] op_sel_hi:[0,1]
	v_pk_mul_f32 v[34:35], v[104:105], v[34:35] op_sel_hi:[0,1]
	v_cvt_pk_bf16_f32 v32, v32, v33
	v_cvt_pk_bf16_f32 v33, v34, v35
	v_lshlrev_b32_e32 v34, 16, v54
	v_and_b32_e32 v35, 0xffff0000, v54
	v_lshlrev_b32_e32 v36, 16, v55
	v_and_b32_e32 v37, 0xffff0000, v55
	v_pk_mul_f32 v[34:35], v[104:105], v[34:35] op_sel_hi:[0,1]
	v_pk_mul_f32 v[36:37], v[104:105], v[36:37] op_sel_hi:[0,1]
	v_cvt_pk_bf16_f32 v34, v34, v35
	v_cvt_pk_bf16_f32 v35, v36, v37
	ds_write_b128 v119, v[32:35] offset:48640
	ds_write_b128 v119, v[56:59] offset:19456
	v_lshlrev_b32_e32 v32, 16, v60
	v_and_b32_e32 v33, 0xffff0000, v60
	v_lshlrev_b32_e32 v34, 16, v61
	v_and_b32_e32 v35, 0xffff0000, v61
	v_pk_mul_f32 v[32:33], v[106:107], v[32:33] op_sel_hi:[0,1]
	v_pk_mul_f32 v[34:35], v[106:107], v[34:35] op_sel_hi:[0,1]
	v_cvt_pk_bf16_f32 v32, v32, v33
	v_cvt_pk_bf16_f32 v33, v34, v35
	v_lshlrev_b32_e32 v34, 16, v62
	v_and_b32_e32 v35, 0xffff0000, v62
	v_lshlrev_b32_e32 v36, 16, v63
	v_and_b32_e32 v37, 0xffff0000, v63
	v_pk_mul_f32 v[34:35], v[106:107], v[34:35] op_sel_hi:[0,1]
	v_pk_mul_f32 v[36:37], v[106:107], v[36:37] op_sel_hi:[0,1]
	v_cvt_pk_bf16_f32 v34, v34, v35
	v_cvt_pk_bf16_f32 v35, v36, v37
	v_lshlrev_b32_e32 v36, 3, v160
	v_and_b32_e32 v150, 24, v36
	ds_write_b128 v119, v[32:35] offset:58368
	v_add3_u32 v120, 0, v149, v150
	v_add3_u32 v121, 0, v151, v150
	s_waitcnt lgkmcnt(0)
	s_barrier
	v_mad_u32_u24 v85, v152, s8, v120
	v_mad_u32_u24 v90, v152, s8, v121
	ds_read_b64_tr_b16 v[38:39], v85 offset:1216
	ds_read_b64_tr_b16 v[36:37], v85
	ds_read_b64_tr_b16 v[40:41], v85 offset:32
	ds_read_b64_tr_b16 v[44:45], v85 offset:64
	ds_read_b64_tr_b16 v[48:49], v85 offset:96
	ds_read_b64_tr_b16 v[54:55], v90 offset:40128
	ds_read_b64_tr_b16 v[52:53], v90 offset:38912
	ds_read_b64_tr_b16 v[42:43], v85 offset:1248
	ds_read_b64_tr_b16 v[46:47], v85 offset:1280
	ds_read_b64_tr_b16 v[50:51], v85 offset:1312
	ds_read_b64_tr_b16 v[58:59], v90 offset:40160
	ds_read_b64_tr_b16 v[56:57], v90 offset:38944
	v_mul_f32_e32 v32, 0, v98
	v_mov_b32_e32 v33, v32
	v_mov_b32_e32 v34, v32
	v_mov_b32_e32 v35, v32
	s_waitcnt lgkmcnt(0)
	s_nop 0
	v_mfma_f32_16x16x32_bf16 v[60:63], v[36:39], v[52:55], v[32:35]
	v_mfma_f32_16x16x32_bf16 v[36:39], v[36:39], v[56:59], v[32:35]
	v_mfma_f32_16x16x32_bf16 v[64:67], v[40:43], v[52:55], v[32:35]
	v_mfma_f32_16x16x32_bf16 v[40:43], v[40:43], v[56:59], v[32:35]
	v_mfma_f32_16x16x32_bf16 v[68:71], v[44:47], v[52:55], v[32:35]
	v_mfma_f32_16x16x32_bf16 v[44:47], v[44:47], v[56:59], v[32:35]
	v_mfma_f32_16x16x32_bf16 v[52:55], v[48:51], v[52:55], v[32:35]
	v_mfma_f32_16x16x32_bf16 v[32:35], v[48:51], v[56:59], v[32:35]
	ds_read_b64_tr_b16 v[50:51], v85 offset:10944
	ds_read_b64_tr_b16 v[48:49], v85 offset:9728
	ds_read_b64_tr_b16 v[56:57], v85 offset:9760
	ds_read_b64_tr_b16 v[72:73], v85 offset:9792
	ds_read_b64_tr_b16 v[76:77], v85 offset:9824
	ds_read_b64_tr_b16 v[80:81], v90 offset:48640
	ds_read_b64_tr_b16 v[82:83], v90 offset:49856
	ds_read_b64_tr_b16 v[58:59], v85 offset:10976
	ds_read_b64_tr_b16 v[74:75], v85 offset:11008
	ds_read_b64_tr_b16 v[78:79], v85 offset:11040
	ds_read_b64_tr_b16 v[88:89], v90 offset:49888
	ds_read_b64_tr_b16 v[86:87], v90 offset:48672
	s_waitcnt lgkmcnt(5)
	v_mfma_f32_16x16x32_bf16 v[60:63], v[48:51], v[80:83], v[60:63]
	s_waitcnt lgkmcnt(0)
	v_mfma_f32_16x16x32_bf16 v[36:39], v[48:51], v[86:89], v[36:39]
	v_mfma_f32_16x16x32_bf16 v[48:51], v[56:59], v[80:83], v[64:67]
	v_mfma_f32_16x16x32_bf16 v[40:43], v[56:59], v[86:89], v[40:43]
	v_mfma_f32_16x16x32_bf16 v[56:59], v[72:75], v[80:83], v[68:71]
	v_mfma_f32_16x16x32_bf16 v[44:47], v[72:75], v[86:89], v[44:47]
	v_mfma_f32_16x16x32_bf16 v[64:67], v[76:79], v[80:83], v[52:55]
	v_mfma_f32_16x16x32_bf16 v[68:71], v[76:79], v[86:89], v[32:35]
	s_nop 2
	ds_read_b64_tr_b16 v[34:35], v85 offset:20672
	ds_read_b64_tr_b16 v[32:33], v85 offset:19456
	ds_read_b64_tr_b16 v[52:53], v85 offset:19488
	ds_read_b64_tr_b16 v[72:73], v85 offset:19520
	ds_read_b64_tr_b16 v[76:77], v85 offset:19552
	ds_read_b64_tr_b16 v[80:81], v90 offset:58368
	ds_read_b64_tr_b16 v[82:83], v90 offset:59584
	ds_read_b64_tr_b16 v[54:55], v85 offset:20704
	ds_read_b64_tr_b16 v[74:75], v85 offset:20736
	ds_read_b64_tr_b16 v[78:79], v85 offset:20768
	ds_read_b64_tr_b16 v[88:89], v90 offset:59616
	ds_read_b64_tr_b16 v[86:87], v90 offset:58400
	s_waitcnt lgkmcnt(5)
	v_mfma_f32_16x16x32_bf16 v[60:63], v[32:35], v[80:83], v[60:63]
	s_waitcnt lgkmcnt(0)
	v_mfma_f32_16x16x32_bf16 v[36:39], v[32:35], v[86:89], v[36:39]
	v_mul_u32_u24_e32 v34, 0xe00, v84
	v_lshl_add_u64 v[32:33], s[4:5], 0, v[96:97]
	v_lshlrev_b32_e32 v116, 1, v34
	v_mfma_f32_16x16x32_bf16 v[108:111], v[52:55], v[86:89], v[40:43]
	v_lshl_add_u64 v[144:145], v[32:33], 0, v[116:117]
	s_mov_b64 s[4:5], 0x38000
	s_nop 0
	v_mov_b32_e32 v40, 0x7200
	v_mad_u32_u24 v40, v152, s8, v40
	v_mfma_f32_16x16x32_bf16 v[48:51], v[52:55], v[80:83], v[48:51]
	global_load_dwordx4 v[202:205], v[144:145], off offset:1024
	global_load_dwordx4 v[206:209], v[144:145], off offset:2048
	v_add_u32_e32 v122, v121, v40
	s_mov_b64 s[8:9], 0x70000
	v_mfma_f32_16x16x32_bf16 v[112:115], v[72:75], v[80:83], v[56:59]
	v_mfma_f32_16x16x32_bf16 v[124:127], v[72:75], v[86:89], v[44:47]
	s_nop 1
	v_lshl_add_u64 v[56:57], v[144:145], 0, s[4:5]
	v_mfma_f32_16x16x32_bf16 v[128:131], v[76:79], v[80:83], v[64:67]
	ds_read_b64_tr_b16 v[42:43], v85 offset:30400
	ds_read_b64_tr_b16 v[40:41], v85 offset:29184
	ds_read_b64_tr_b16 v[44:45], v85 offset:29216
	ds_read_b64_tr_b16 v[80:81], v85 offset:29248
	ds_read_b64_tr_b16 v[132:133], v85 offset:29280
	ds_read_b64_tr_b16 v[138:139], v122 offset:40128
	ds_read_b64_tr_b16 v[136:137], v122 offset:38912
	ds_read_b64_tr_b16 v[46:47], v85 offset:30432
	ds_read_b64_tr_b16 v[82:83], v85 offset:30464
	ds_read_b64_tr_b16 v[134:135], v85 offset:30496
	ds_read_b64_tr_b16 v[142:143], v122 offset:40160
	ds_read_b64_tr_b16 v[140:141], v122 offset:38944
	v_mfma_f32_16x16x32_bf16 v[88:91], v[76:79], v[86:89], v[68:71]
	s_waitcnt lgkmcnt(4)
	v_mfma_f32_16x16x32_bf16 v[68:71], v[44:47], v[136:139], v[48:51]
	s_nop 2
	v_lshl_add_u64 v[48:49], v[144:145], 0, s[8:9]
	v_mfma_f32_16x16x32_bf16 v[92:95], v[40:43], v[136:139], v[60:63]
	s_waitcnt lgkmcnt(0)
	v_mfma_f32_16x16x32_bf16 v[64:67], v[40:43], v[140:143], v[36:39]
	s_nop 2
	global_load_dwordx4 v[210:213], v[56:57], off offset:1024
	global_load_dwordx4 v[214:217], v[56:57], off offset:2048
	global_load_dwordx4 v[218:221], v[48:49], off offset:1024
	s_nop 0
	global_load_dwordx4 v[222:225], v[48:49], off offset:2048
	v_lshl_add_u64 v[48:49], v[144:145], 0, s[10:11]
	v_mfma_f32_16x16x32_bf16 v[72:75], v[44:47], v[140:143], v[108:111]
	global_load_dwordx4 v[226:229], v[48:49], off offset:1024
	s_nop 0
	global_load_dwordx4 v[230:233], v[48:49], off offset:2048
	v_mov_b32_e32 v108, v98
	v_mov_b32_e32 v109, v98
	v_mfma_f32_16x16x32_bf16 v[76:79], v[80:83], v[136:139], v[112:115]
	v_mfma_f32_16x16x32_bf16 v[80:83], v[80:83], v[140:143], v[124:127]
	v_mfma_f32_16x16x32_bf16 v[84:87], v[132:135], v[136:139], v[128:131]
	s_nop 1
	v_mul_u32_u24_e32 v124, 0x130, v152
	v_mfma_f32_16x16x32_bf16 v[88:91], v[132:135], v[140:143], v[88:91]
	s_lshl_b32 s14, s14, 5
	v_and_or_b32 v99, v148, 16, v99
	s_or_b32 s14, s15, s14
	v_lshlrev_b32_e32 v110, 4, v99
	v_mov_b32_e32 v111, v97
	v_lshrrev_b32_e32 v99, 1, v160
	s_add_i32 s17, 0, 0x13000
	s_or_b32 s12, s14, s12
	v_lshl_add_u64 v[110:111], s[22:23], 0, v[110:111]
	v_and_b32_e32 v112, 8, v99
	v_mov_b32_e32 v113, v97
	v_add_u32_e32 v115, s17, v96
	s_add_i32 s28, 0, 0x1c800
	v_add3_u32 v127, s17, v149, v150
	s_lshl_b32 s17, s12, 5
	v_lshl_add_u64 v[110:111], v[110:111], 0, v[112:113]
	s_mov_b64 s[14:15], 0x154bc000
	v_lshl_add_u64 v[110:111], v[110:111], 0, s[14:15]
	v_lshlrev_b32_e32 v99, 10, v147
	s_add_u32 s14, s25, s24
	v_lshl_or_b32 v114, v146, 12, v99
	s_addc_u32 s15, s27, 0
	v_add_u32_e32 v126, s28, v96
	v_add3_u32 v128, s28, v151, v150
	v_add_u32_e32 v130, 0x900, v114
	v_add_u32_e32 v132, 0xb00, v114
	v_lshl_add_u64 v[112:113], s[14:15], 0, v[96:97]
	v_lshl_add_u64 v[112:113], v[112:113], 0, v[116:117]
	s_mov_b32 s24, 30
	v_add_u32_e32 v125, v115, v123
	v_add_u32_e32 v126, v126, v123
	v_add_u32_e32 v127, v127, v124
	v_add_u32_e32 v128, v128, v124
	v_lshlrev_b32_e32 v96, 1, v114
	s_movk_i32 s25, 0x1000
	v_lshlrev_b32_e32 v114, 1, v130
	v_lshlrev_b32_e32 v116, 1, v132
	v_mov_b32_e32 v129, 0x1c00
	v_readfirstlane_b32 s98, v160
	s_nop 3
	s_lshr_b32 s98, s98, 8
	s_cmp_eq_u32 s98, 0
	s_cbranch_scc0 .Lchain_prio_done
	s_setprio 1
